# hand-written gemm_out epilogue (16 residual loads in flight per half); gemm_out gets the k-blocked W_out + 3-stage interleaved loop; first inter-phase barrier uses the XCD barrier instead of the coope
# speedup vs baseline: 1.0330x; 1.0330x over previous
; __device__ __forceinline__ void xcd_barrier(const XcdBarrier& b) {
;   asm volatile("s_waitcnt vmcnt(0)" ::: "memory");
;   __syncthreads();
;   if (threadIdx.x == 0) {
;     unsigned* bar = b.bar;
;     __builtin_amdgcn_s_waitcnt(0);
;     unsigned nloc = b.st[0], nx = b.st[1];
;     if (nloc == 0u) { xcd_barrier_complete(bar, b.x, nloc, nx); b.st[0] = nloc; b.st[1] = nx; }
; __global__ void __launch_bounds__(256, 2) mega(Params p) {
;     ...
;   for (int ph = p.phase_lo; ph < p.phase_hi; ++ph) {
;     if (ph > p.phase_lo) {
;       if (ph == p.phase_lo + 1) grid.sync();
;       else xcd_barrier(xb);
;     }
;     run_phase(p, ph, smem);
.LBB0_11:
	s_cmp_le_i32 s8, s6
	v_writelane_b32 v248, s8, 36
	s_cbranch_scc1 .LBB0_75
	v_readlane_b32 s4, v249, 5
	v_readlane_b32 s5, v248, 36
	s_cmp_lg_u32 s5, s4
	s_mov_b64 s[30:31], -1
	s_waitcnt vmcnt(0)
	v_readlane_b32 s4, v248, 24
	v_readlane_b32 s5, v248, 25
	s_barrier
	s_and_saveexec_b64 s[30:31], s[4:5]
	s_cbranch_execz .LBB0_61
	v_readlane_b32 s4, v248, 14
	s_waitcnt vmcnt(0) expcnt(0) lgkmcnt(0)
	s_nop 0
	v_mov_b32_e32 v0, s4
	ds_read_b32 v2, v0
	v_readlane_b32 s4, v248, 15
	s_waitcnt lgkmcnt(0)
	v_cmp_ne_u32_e32 vcc, 0, v2
	v_mov_b32_e32 v0, s4
	ds_read_b32 v0, v0
	s_cbranch_vccnz .LBB0_29
	s_mov_b32 s36, 1
	s_branch .LBB0_17

; __device__ void run_phase(const Params& p, int ph, unsigned char* smem) {
;   if (ph == 0) { phase_prep(p, smem); return; }
;   if (ph == NPHASE - 1) { phase_norm(p, 0, true); return; }
;   const int l = (ph - 1) / 7, s = (ph - 1) % 7;
; __device__ __forceinline__ void xcd_barrier(const XcdBarrier& b) {
;     ...
;     }
;   }
;   __syncthreads();
.LBB0_61:
	s_or_b64 exec, exec, s[30:31]
	s_mov_b64 s[30:31], 0
	s_waitcnt lgkmcnt(0)
	s_barrier
.LBB0_74:
.LBB0_75:
	v_readlane_b32 s4, v248, 36
	s_mov_b64 s[40:41], -1
	s_mov_b64 s[30:31], 0
	s_cmp_lt_i32 s4, 15
	s_mov_b64 s[38:39], 0
	s_cbranch_scc0 .LBB0_79
	s_and_b64 vcc, exec, s[40:41]
	s_cbranch_vccnz .LBB0_93

; __device__ __forceinline__ int TIDX() { int t = threadIdx.x; asm volatile("" : "+v"(t)); return t; }
; #define ISSUE_TILE(kt_, stg_) do { \
;     unsigned char* sb_ = wbase + (stg_) * STG; const u16* pa_ = ga + (kt_) * 32; const u16* pb_ = gb + (kt_) * 32; \
;     GLDS16(pa_, sb_); GLDS16(pa_ + sa64, sb_ + 4096); \
;     GLDS16(pb_, sb_ + 8192); GLDS16(pb_ + sb64, sb_ + 8192 + 4096); \
;     GLDS16(pb_ + 2 * sb64, sb_ + 8192 + 8192); GLDS16(pb_ + 3 * sb64, sb_ + 8192 + 12288); } while (0)
; __device__ __forceinline__ void gemm_mainloop3(const u16* __restrict__ A, int lda, const u16* __restrict__ B, int ldb,
;                                                int K, f32x4 (&acc)[4][8], unsigned char* smb) {
;   const int tid = TIDX(), lane = tid & 63, w = tid >> 6, wm = w >> 1, wn = w & 1, l15 = lane & 15, g = lane >> 4;
;   constexpr int STG = 24576;
;   const int rowt = tid >> 2;
;   const int cl = ((tid & 3) ^ (((tid >> 5) & 1) << 1)) * 8;
;   const u16* ga = A + (size_t)rowt * lda + cl;
;   const u16* gb = B + (size_t)rowt * ldb + cl;
;   const size_t sa64 = (size_t)64 * lda, sb64 = (size_t)64 * ldb;
;   unsigned char* wbase = smb + w * 1024;
;     ...
;   ISSUE_TILE(0, 0);
;   asm volatile("s_waitcnt vmcnt(0)" ::: "memory");
;   __syncthreads();
;   const int csw = (g ^ (((l15 >> 3) & 1) << 1)) * 16;
;   const int nk = K >> 5;
;   for (int kt = 0; kt < nk; ++kt) {
;     const int cur = kt & 1;
;     if (kt + 1 < nk) ISSUE_TILE(kt + 1, cur ^ 1);
; __device__ void phase_gemm_out(const Params& p, int l, unsigned char* smem, bool dry = false) {
;   const int ntn = DM / 256;
;   u16* H1B = p.Z;
;   float* ct = (float*)smem;
;   TileIter it = tile_iter((T_TOK / 128) * ntn);
;   for (int v = it.v; v < it.end; v += it.step) {
;     int m0, n0; tile_mn(v, ntn, 256, m0, n0);
;     f32x4 acc[4][8];
; #pragma unroll
;     for (int a = 0; a < 4; ++a)
; #pragma unroll
;       for (int b = 0; b < 8; ++b) acc[a][b] = f32x4{0.f, 0.f, 0.f, 0.f};
;     gemm_mainloop3(p.ACT + (size_t)m0 * DM, DM, p.WOUT + (size_t)l * DM * DM + (size_t)n0 * DM, DM, DM, acc, smem);
.LBB0_118:
	s_ashr_i32 s40, s36, 31
	s_lshr_b32 s40, s40, 27
	s_add_i32 s40, s36, s40
	s_and_b32 s41, s40, 0xffffffe0
	s_sub_i32 s41, s36, s41
	s_lshl_b32 s42, s41, 7
	s_lshl_b32 s40, s40, 5
	s_and_b32 s42, s42, 0x380
	s_and_b32 s40, s40, 0xfffffc00
	s_or_b32 s46, s42, s40
	s_lshl_b32 s41, s41, 5
	s_ashr_i32 s47, s46, 31
	v_mov_b32_e32 v6, v147
	s_and_b32 s42, s41, 0xffffff00
	s_lshl_b64 s[40:41], s[46:47], 11
	s_add_u32 s50, s80, s40
	v_ashrrev_i32_e32 v0, 2, v6
	v_and_b32_e32 v1, 3, v6
	v_lshrrev_b32_e32 v2, 4, v6
	v_ashrrev_i32_e32 v7, 6, v6
	v_bitop3_b32 v4, v2, v1, 2 bitop3:0x6c
	v_ashrrev_i32_e32 v1, 31, v0
	s_addc_u32 s51, s81, s41
	s_ashr_i32 s43, s42, 31
	v_lshlrev_b64 v[0:1], 11, v[0:1]
	v_lshl_add_u32 v132, v7, 10, 0
	s_lshl_b64 s[52:53], s[42:43], 6
	v_lshl_add_u64 v[2:3], s[50:51], 0, v[0:1]
	v_lshlrev_b32_e32 v144, 4, v4
	v_readfirstlane_b32 s43, v132
	v_add_u32_e32 v9, 0x1000, v132
	v_lshl_add_u64 v[2:3], v[2:3], 0, v[144:145]
	s_mov_b32 m0, s43
	s_mov_b64 s[4:5], 0x20000
	v_readfirstlane_b32 s43, v9
	s_add_u32 s54, s44, s52
	global_load_lds_dwordx4 v[2:3], off
	v_lshl_add_u64 v[2:3], v[2:3], 0, s[4:5]
	s_mov_b32 m0, s43
	s_addc_u32 s55, s45, s53
	global_load_lds_dwordx4 v[2:3], off
	v_add_u32_e32 v2, 0x2000, v132
	v_lshrrev_b32_e32 v10, 2, v6
	v_lshlrev_b32_e32 v10, 6, v10
	v_mov_b32_e32 v11, 0
	v_lshl_add_u64 v[4:5], s[54:55], 0, v[10:11]
	v_readfirstlane_b32 s43, v2
	v_add_u32_e32 v9, 0x3000, v132
	v_lshl_add_u64 v[4:5], v[4:5], 0, v[144:145]
	v_mov_b32_e32 v130, v4
	v_mov_b32_e32 v131, v5
	s_mov_b32 m0, s43
	v_readfirstlane_b32 s43, v9
	v_add_u32_e32 v9, 0x4000, v132
	global_load_lds_dwordx4 v[4:5], off
	s_mov_b64 s[4:5], 0x1000
	v_lshl_add_u64 v[2:3], v[4:5], 0, s[4:5]
	s_mov_b32 m0, s43
	s_mov_b64 s[4:5], 0x2000
	v_readfirstlane_b32 s43, v9
	global_load_lds_dwordx4 v[2:3], off
	v_lshl_add_u64 v[2:3], v[4:5], 0, s[4:5]
	s_mov_b32 m0, s43
	s_mov_b64 s[4:5], 0x3000
	global_load_lds_dwordx4 v[2:3], off
	v_lshl_add_u64 v[2:3], v[4:5], 0, s[4:5]
	v_add_u32_e32 v4, 0x5000, v132
	v_and_b32_e32 v8, 15, v6
	v_readfirstlane_b32 s43, v4
	s_mov_b32 m0, s43
	s_mov_b32 s4, 0x3ffffc0
	global_load_lds_dwordx4 v[2:3], off
	v_lshlrev_b32_e32 v2, 2, v6
	v_and_b32_e32 v3, 48, v6
	v_bitop3_b32 v133, v2, v3, 32 bitop3:0x6c
	v_lshrrev_b32_e32 v2, 1, v6
	v_and_or_b32 v2, v2, s4, v8
	v_lshlrev_b32_e32 v134, 6, v2
	v_lshlrev_b32_e32 v2, 7, v7
	s_movk_i32 s4, 0x80
	v_and_or_b32 v2, v2, s4, v8
	v_lshlrev_b32_e32 v135, 6, v2
	v_lshl_add_u64 v[2:3], v[0:1], 0, s[40:41]
	v_or_b32_e32 v2, v2, v144
	v_mov_b32_e32 v60, 0
	v_lshl_add_u64 v[128:129], s[80:81], 0, v[2:3]
	s_mov_b64 s[4:5], 0x1000
	v_readfirstlane_b32 s43, v132
	v_lshl_add_u64 v[166:167], v[130:131], 0, s[4:5]
	s_mov_b64 s[4:5], 0x2000
	s_mov_b32 s47, 0
	v_lshl_add_u64 v[168:169], v[130:131], 0, s[4:5]
	s_mov_b64 s[4:5], 0x3000
	s_mov_b32 s50, 0x10000
	v_lshl_add_u64 v[170:171], v[130:131], 0, s[4:5]
	s_mov_b32 s51, 0
	s_mov_b64 s[40:41], 0
	v_mov_b32_e32 v61, v60
	v_mov_b32_e32 v62, v60
	v_mov_b32_e32 v63, v60
	v_mov_b32_e32 v20, v60
	v_mov_b32_e32 v21, v60
	v_mov_b32_e32 v22, v60
	v_mov_b32_e32 v23, v60
	v_mov_b32_e32 v8, v60
	v_mov_b32_e32 v9, v60
	v_mov_b32_e32 v10, v60
	v_mov_b32_e32 v11, v60
	v_mov_b32_e32 v0, v60
	v_mov_b32_e32 v1, v60
	v_mov_b32_e32 v2, v60
	v_mov_b32_e32 v3, v60
	v_mov_b32_e32 v4, v60
	v_mov_b32_e32 v5, v60
	v_mov_b32_e32 v6, v60
	v_mov_b32_e32 v7, v60
	v_mov_b32_e32 v12, v60
	v_mov_b32_e32 v13, v60
	v_mov_b32_e32 v14, v60
	v_mov_b32_e32 v15, v60
	v_mov_b32_e32 v24, v60
	v_mov_b32_e32 v25, v60
	v_mov_b32_e32 v26, v60
	v_mov_b32_e32 v27, v60
	v_mov_b32_e32 v36, v60
	v_mov_b32_e32 v37, v60
	v_mov_b32_e32 v38, v60
	v_mov_b32_e32 v39, v60
	v_mov_b32_e32 v44, v60
	v_mov_b32_e32 v45, v60
	v_mov_b32_e32 v46, v60
	v_mov_b32_e32 v47, v60
	v_mov_b32_e32 v32, v60
	v_mov_b32_e32 v33, v60
	v_mov_b32_e32 v34, v60
	v_mov_b32_e32 v35, v60
	v_mov_b32_e32 v16, v60
	v_mov_b32_e32 v17, v60
	v_mov_b32_e32 v18, v60
	v_mov_b32_e32 v19, v60
	v_mov_b32_e32 v28, v60
	v_mov_b32_e32 v29, v60
	v_mov_b32_e32 v30, v60
	v_mov_b32_e32 v31, v60
	v_mov_b32_e32 v40, v60
	v_mov_b32_e32 v41, v60
	v_mov_b32_e32 v42, v60
	v_mov_b32_e32 v43, v60
	v_mov_b32_e32 v48, v60
	v_mov_b32_e32 v49, v60
	v_mov_b32_e32 v50, v60
	v_mov_b32_e32 v51, v60
	v_mov_b32_e32 v68, v60
	v_mov_b32_e32 v69, v60
	v_mov_b32_e32 v70, v60
	v_mov_b32_e32 v71, v60
	v_mov_b32_e32 v80, v60
	v_mov_b32_e32 v81, v60
	v_mov_b32_e32 v82, v60
	v_mov_b32_e32 v83, v60
	v_mov_b32_e32 v52, v60
	v_mov_b32_e32 v53, v60
	v_mov_b32_e32 v54, v60
	v_mov_b32_e32 v55, v60
	v_mov_b32_e32 v56, v60
	v_mov_b32_e32 v57, v60
	v_mov_b32_e32 v58, v60
	v_mov_b32_e32 v59, v60
	v_mov_b32_e32 v64, v60
	v_mov_b32_e32 v65, v60
	v_mov_b32_e32 v66, v60
	v_mov_b32_e32 v67, v60
	v_mov_b32_e32 v72, v60
	v_mov_b32_e32 v73, v60
	v_mov_b32_e32 v74, v60
	v_mov_b32_e32 v75, v60
	v_mov_b32_e32 v84, v60
	v_mov_b32_e32 v85, v60
	v_mov_b32_e32 v86, v60
	v_mov_b32_e32 v87, v60
	v_mov_b32_e32 v92, v60
	v_mov_b32_e32 v93, v60
	v_mov_b32_e32 v94, v60
	v_mov_b32_e32 v95, v60
	v_mov_b32_e32 v100, v60
	v_mov_b32_e32 v101, v60
	v_mov_b32_e32 v102, v60
	v_mov_b32_e32 v103, v60
	v_mov_b32_e32 v108, v60
	v_mov_b32_e32 v109, v60
	v_mov_b32_e32 v110, v60
	v_mov_b32_e32 v111, v60
	v_mov_b32_e32 v76, v60
	v_mov_b32_e32 v77, v60
	v_mov_b32_e32 v78, v60
	v_mov_b32_e32 v79, v60
	v_mov_b32_e32 v88, v60
	v_mov_b32_e32 v89, v60
	v_mov_b32_e32 v90, v60
	v_mov_b32_e32 v91, v60
	v_mov_b32_e32 v96, v60
	v_mov_b32_e32 v97, v60
	v_mov_b32_e32 v98, v60
	v_mov_b32_e32 v99, v60
	v_mov_b32_e32 v104, v60
	v_mov_b32_e32 v105, v60
	v_mov_b32_e32 v106, v60
	v_mov_b32_e32 v107, v60
	v_mov_b32_e32 v112, v60
	v_mov_b32_e32 v113, v60
	v_mov_b32_e32 v114, v60
	v_mov_b32_e32 v115, v60
	v_mov_b32_e32 v116, v60
	v_mov_b32_e32 v117, v60
	v_mov_b32_e32 v118, v60
	v_mov_b32_e32 v119, v60
	v_mov_b32_e32 v120, v60
	v_mov_b32_e32 v121, v60
	v_mov_b32_e32 v122, v60
	v_mov_b32_e32 v123, v60
	v_mov_b32_e32 v124, v60
	v_mov_b32_e32 v125, v60
	v_mov_b32_e32 v126, v60
	v_mov_b32_e32 v127, v60
	s_add_i32 m0, s43, 0x6000
	v_lshl_add_u64 v[172:173], v[128:129], 0, 64
	global_load_lds_dwordx4 v[172:173], off
	s_add_i32 m0, m0, 0x1000
	v_lshl_add_u64 v[174:175], v[128:129], 0, s[34:35]
	global_load_lds_dwordx4 v[174:175], off
	s_add_i32 m0, m0, 0x1000
	v_lshl_add_u64 v[172:173], v[130:131], 0, s[50:51]
	global_load_lds_dwordx4 v[172:173], off
	s_add_i32 m0, m0, 0x1000
	v_lshl_add_u64 v[174:175], v[166:167], 0, s[50:51]
	global_load_lds_dwordx4 v[174:175], off
	s_add_i32 m0, m0, 0x1000
	v_lshl_add_u64 v[172:173], v[168:169], 0, s[50:51]
	global_load_lds_dwordx4 v[172:173], off
	s_add_i32 m0, m0, 0x1000
	v_lshl_add_u64 v[174:175], v[170:171], 0, s[50:51]
	global_load_lds_dwordx4 v[174:175], off
	v_lshl_add_u64 v[128:129], v[128:129], 0, 64
	s_add_i32 s50, s50, 0x10000
	s_mov_b32 s52, 0xc000
	s_waitcnt vmcnt(6) lgkmcnt(0)
	s_barrier
; #define ISSUE_TILE(kt_, stg_) do { \
;     unsigned char* sb_ = wbase + (stg_) * STG; const u16* pa_ = ga + (kt_) * 32; const u16* pb_ = gb + (kt_) * 32; \
;     GLDS16(pa_, sb_); GLDS16(pa_ + sa64, sb_ + 4096); \
;     GLDS16(pb_, sb_ + 8192); GLDS16(pb_ + sb64, sb_ + 8192 + 4096); \
;     GLDS16(pb_ + 2 * sb64, sb_ + 8192 + 8192); GLDS16(pb_ + 3 * sb64, sb_ + 8192 + 12288); } while (0)
; __device__ __forceinline__ void gemm_mainloop3(const u16* __restrict__ A, int lda, const u16* __restrict__ B, int ldb,
;                                                int K, f32x4 (&acc)[4][8], unsigned char* smb) {
;     ...
;   for (int kt = 0; kt < nk; ++kt) {
;     const int cur = kt & 1;
;     if (kt + 1 < nk) ISSUE_TILE(kt + 1, cur ^ 1);
;     __builtin_amdgcn_sched_barrier(0);
;     const unsigned char* cA = smb + cur * STG + (wm * 64 + l15) * 64 + csw;
;     const unsigned char* cB = smb + cur * STG + 8192 + (wn * 128 + l15) * 64 + csw;
;     bf16x8 af[4];
; #pragma unroll
;     for (int i = 0; i < 4; ++i) af[i] = *(const bf16x8*)(cA + i * 16 * 64);
; #pragma unroll
;     for (int nh = 0; nh < 2; ++nh) {
;       bf16x8 bfr[4];
; #pragma unroll
;       for (int i = 0; i < 4; ++i) bfr[i] = *(const bf16x8*)(cB + (nh * 4 + i) * 16 * 64);
; #pragma unroll
;       for (int nt = 0; nt < 4; ++nt)
; #pragma unroll
;         for (int mt = 0; mt < 4; ++mt) acc[mt][nh * 4 + nt] = mfma16(bfr[nt], af[mt], acc[mt][nh * 4 + nt]);
;     }
;     __builtin_amdgcn_sched_group_barrier(0x100, 6, 0);
; #pragma unroll
;     for (int i = 0; i < 6; ++i) {
;       __builtin_amdgcn_sched_group_barrier(0x008, 4, 0);
;       __builtin_amdgcn_sched_group_barrier(0x100, 1, 0);
;     }
;     __builtin_amdgcn_sched_group_barrier(0x008, 8, 0);
;     __builtin_amdgcn_sched_barrier(0);
;     asm volatile("s_waitcnt vmcnt(0)" ::: "memory");
;     __syncthreads();
;   }
.LBB0_119:
	v_add3_u32 v144, s47, v135, v133
	ds_read_b128 v[136:139], v144 offset:8192
	ds_read_b128 v[162:165], v144 offset:9216
	v_add3_u32 v149, s47, v134, v133
	ds_read_b128 v[140:143], v149
	ds_read_b128 v[150:153], v149 offset:1024
	ds_read_b128 v[154:157], v149 offset:2048
	ds_read_b128 v[158:161], v149 offset:3072
	s_add_i32 m0, s43, s52
	v_lshl_add_u64 v[172:173], v[128:129], 0, s[40:41]
	v_lshl_add_u64 v[174:175], v[172:173], 0, 64
	global_load_lds_dwordx4 v[174:175], off
	s_waitcnt lgkmcnt(0)
	v_mfma_f32_16x16x32_bf16 v[124:127], v[136:139], v[140:143], v[124:127]
	v_mfma_f32_16x16x32_bf16 v[108:111], v[136:139], v[150:153], v[108:111]
	v_mfma_f32_16x16x32_bf16 v[80:83], v[136:139], v[154:157], v[80:83]
	v_mfma_f32_16x16x32_bf16 v[36:39], v[136:139], v[158:161], v[36:39]
	ds_read_b128 v[136:139], v144 offset:10240
	s_add_i32 m0, m0, 0x1000
	v_lshl_add_u64 v[172:173], v[172:173], 0, s[34:35]
	global_load_lds_dwordx4 v[172:173], off
	v_mfma_f32_16x16x32_bf16 v[120:123], v[162:165], v[140:143], v[120:123]
	v_mfma_f32_16x16x32_bf16 v[100:103], v[162:165], v[150:153], v[100:103]
	v_mfma_f32_16x16x32_bf16 v[68:71], v[162:165], v[154:157], v[68:71]
	v_mfma_f32_16x16x32_bf16 v[24:27], v[162:165], v[158:161], v[24:27]
	ds_read_b128 v[162:165], v144 offset:11264
	s_add_i32 m0, m0, 0x1000
	v_lshl_add_u64 v[174:175], v[130:131], 0, s[50:51]
	global_load_lds_dwordx4 v[174:175], off
	s_waitcnt lgkmcnt(0)
	v_mfma_f32_16x16x32_bf16 v[116:119], v[136:139], v[140:143], v[116:119]
	v_mfma_f32_16x16x32_bf16 v[92:95], v[136:139], v[150:153], v[92:95]
	v_mfma_f32_16x16x32_bf16 v[48:51], v[136:139], v[154:157], v[48:51]
	v_mfma_f32_16x16x32_bf16 v[12:15], v[136:139], v[158:161], v[12:15]
	ds_read_b128 v[136:139], v144 offset:12288
	s_add_i32 m0, m0, 0x1000
	v_lshl_add_u64 v[172:173], v[166:167], 0, s[50:51]
	global_load_lds_dwordx4 v[172:173], off
	v_mfma_f32_16x16x32_bf16 v[112:115], v[162:165], v[140:143], v[112:115]
	v_mfma_f32_16x16x32_bf16 v[84:87], v[162:165], v[150:153], v[84:87]
	v_mfma_f32_16x16x32_bf16 v[40:43], v[162:165], v[154:157], v[40:43]
	v_mfma_f32_16x16x32_bf16 v[4:7], v[162:165], v[158:161], v[4:7]
	ds_read_b128 v[162:165], v144 offset:13312
	s_add_i32 m0, m0, 0x1000
	v_lshl_add_u64 v[174:175], v[168:169], 0, s[50:51]
	global_load_lds_dwordx4 v[174:175], off
	s_waitcnt lgkmcnt(0)
	v_mfma_f32_16x16x32_bf16 v[104:107], v[136:139], v[140:143], v[104:107]
	v_mfma_f32_16x16x32_bf16 v[72:75], v[136:139], v[150:153], v[72:75]
	v_mfma_f32_16x16x32_bf16 v[28:31], v[136:139], v[154:157], v[28:31]
	v_mfma_f32_16x16x32_bf16 v[0:3], v[136:139], v[158:161], v[0:3]
	ds_read_b128 v[136:139], v144 offset:14336
	s_add_i32 m0, m0, 0x1000
	v_lshl_add_u64 v[172:173], v[170:171], 0, s[50:51]
	global_load_lds_dwordx4 v[172:173], off
	v_mfma_f32_16x16x32_bf16 v[96:99], v[162:165], v[140:143], v[96:99]
	v_mfma_f32_16x16x32_bf16 v[64:67], v[162:165], v[150:153], v[64:67]
	v_mfma_f32_16x16x32_bf16 v[16:19], v[162:165], v[154:157], v[16:19]
	v_mfma_f32_16x16x32_bf16 v[8:11], v[162:165], v[158:161], v[8:11]
	ds_read_b128 v[162:165], v144 offset:15360
	s_waitcnt lgkmcnt(0)
	v_mfma_f32_16x16x32_bf16 v[88:91], v[136:139], v[140:143], v[88:91]
	v_mfma_f32_16x16x32_bf16 v[56:59], v[136:139], v[150:153], v[56:59]
	v_mfma_f32_16x16x32_bf16 v[32:35], v[136:139], v[154:157], v[32:35]
	v_mfma_f32_16x16x32_bf16 v[20:23], v[136:139], v[158:161], v[20:23]
	v_mfma_f32_16x16x32_bf16 v[76:79], v[162:165], v[140:143], v[76:79]
	v_mfma_f32_16x16x32_bf16 v[52:55], v[162:165], v[150:153], v[52:55]
	v_mfma_f32_16x16x32_bf16 v[44:47], v[162:165], v[154:157], v[44:47]
	v_mfma_f32_16x16x32_bf16 v[60:63], v[162:165], v[158:161], v[60:63]
	s_add_u32 s40, s40, 64
	s_addc_u32 s41, s41, 0
	s_add_i32 s50, s50, 0x10000
	s_add_i32 s47, s47, 0x6000
	s_cmp_eq_u32 s47, 0x12000
	s_cselect_b32 s47, 0, s47
	s_add_i32 s52, s52, 0x6000
	s_cmp_eq_u32 s52, 0x12000
	s_cselect_b32 s52, 0, s52
	s_cmpk_lg_i32 s40, 0x780
	s_waitcnt vmcnt(6)
	s_barrier
	s_cbranch_scc1 .LBB0_119
	v_add3_u32 v144, 0, v135, v133
	ds_read_b128 v[136:139], v144 offset:8192
	ds_read_b128 v[162:165], v144 offset:9216
	v_add3_u32 v149, 0, v134, v133
	ds_read_b128 v[140:143], v149
	ds_read_b128 v[150:153], v149 offset:1024
	ds_read_b128 v[154:157], v149 offset:2048
	ds_read_b128 v[158:161], v149 offset:3072
	s_waitcnt lgkmcnt(0)
	v_mfma_f32_16x16x32_bf16 v[124:127], v[136:139], v[140:143], v[124:127]
	v_mfma_f32_16x16x32_bf16 v[108:111], v[136:139], v[150:153], v[108:111]
	v_mfma_f32_16x16x32_bf16 v[80:83], v[136:139], v[154:157], v[80:83]
	v_mfma_f32_16x16x32_bf16 v[36:39], v[136:139], v[158:161], v[36:39]
	ds_read_b128 v[136:139], v144 offset:10240
	v_mfma_f32_16x16x32_bf16 v[120:123], v[162:165], v[140:143], v[120:123]
	v_mfma_f32_16x16x32_bf16 v[100:103], v[162:165], v[150:153], v[100:103]
	v_mfma_f32_16x16x32_bf16 v[68:71], v[162:165], v[154:157], v[68:71]
	v_mfma_f32_16x16x32_bf16 v[24:27], v[162:165], v[158:161], v[24:27]
	ds_read_b128 v[162:165], v144 offset:11264
	s_waitcnt lgkmcnt(0)
	v_mfma_f32_16x16x32_bf16 v[116:119], v[136:139], v[140:143], v[116:119]
	v_mfma_f32_16x16x32_bf16 v[92:95], v[136:139], v[150:153], v[92:95]
	v_mfma_f32_16x16x32_bf16 v[48:51], v[136:139], v[154:157], v[48:51]
	v_mfma_f32_16x16x32_bf16 v[12:15], v[136:139], v[158:161], v[12:15]
	ds_read_b128 v[136:139], v144 offset:12288
	v_mfma_f32_16x16x32_bf16 v[112:115], v[162:165], v[140:143], v[112:115]
	v_mfma_f32_16x16x32_bf16 v[84:87], v[162:165], v[150:153], v[84:87]
	v_mfma_f32_16x16x32_bf16 v[40:43], v[162:165], v[154:157], v[40:43]
	v_mfma_f32_16x16x32_bf16 v[4:7], v[162:165], v[158:161], v[4:7]
	ds_read_b128 v[162:165], v144 offset:13312
	s_waitcnt lgkmcnt(0)
	v_mfma_f32_16x16x32_bf16 v[104:107], v[136:139], v[140:143], v[104:107]
	v_mfma_f32_16x16x32_bf16 v[72:75], v[136:139], v[150:153], v[72:75]
	v_mfma_f32_16x16x32_bf16 v[28:31], v[136:139], v[154:157], v[28:31]
	v_mfma_f32_16x16x32_bf16 v[0:3], v[136:139], v[158:161], v[0:3]
	ds_read_b128 v[136:139], v144 offset:14336
	v_mfma_f32_16x16x32_bf16 v[96:99], v[162:165], v[140:143], v[96:99]
	v_mfma_f32_16x16x32_bf16 v[64:67], v[162:165], v[150:153], v[64:67]
	v_mfma_f32_16x16x32_bf16 v[16:19], v[162:165], v[154:157], v[16:19]
	v_mfma_f32_16x16x32_bf16 v[8:11], v[162:165], v[158:161], v[8:11]
	ds_read_b128 v[162:165], v144 offset:15360
	s_waitcnt lgkmcnt(0)
	v_mfma_f32_16x16x32_bf16 v[88:91], v[136:139], v[140:143], v[88:91]
	v_mfma_f32_16x16x32_bf16 v[56:59], v[136:139], v[150:153], v[56:59]
	v_mfma_f32_16x16x32_bf16 v[32:35], v[136:139], v[154:157], v[32:35]
	v_mfma_f32_16x16x32_bf16 v[20:23], v[136:139], v[158:161], v[20:23]
	v_mfma_f32_16x16x32_bf16 v[76:79], v[162:165], v[140:143], v[76:79]
	v_mfma_f32_16x16x32_bf16 v[52:55], v[162:165], v[150:153], v[52:55]
	v_mfma_f32_16x16x32_bf16 v[44:47], v[162:165], v[154:157], v[44:47]
	v_mfma_f32_16x16x32_bf16 v[60:63], v[162:165], v[158:161], v[60:63]
	s_waitcnt vmcnt(0)
	s_barrier
; __device__ __forceinline__ int TIDX() { int t = threadIdx.x; asm volatile("" : "+v"(t)); return t; }
; __device__ __forceinline__ void gemm_mainloop3(const u16* __restrict__ A, int lda, const u16* __restrict__ B, int ldb,
;                                                int K, f32x4 (&acc)[4][8], unsigned char* smb) {
;     ...
; #pragma unroll
;     for (int i = 0; i < 4; ++i) af[i] = *(const bf16x8*)(cA + i * 16 * 64);
; #pragma unroll
;     for (int nh = 0; nh < 2; ++nh) {
;       bf16x8 bfr[4];
; #pragma unroll
;       for (int i = 0; i < 4; ++i) bfr[i] = *(const bf16x8*)(cB + (nh * 4 + i) * 16 * 64);
; #pragma unroll
;       for (int nt = 0; nt < 4; ++nt)
; #pragma unroll
;         for (int mt = 0; mt < 4; ++mt) acc[mt][nh * 4 + nt] = mfma16(bfr[nt], af[mt], acc[mt][nh * 4 + nt]);
;     }
; __device__ __forceinline__ void acc2_to_lds(const f32x4 (&acc)[4][8], float* ct, int hf) {
;   const int tid = TIDX(), lane = tid & 63, w = tid >> 6, wm = w >> 1, wn = w & 1, l15 = lane & 15, g = lane >> 4;
; #pragma unroll
;   for (int mt = 0; mt < 4; ++mt)
; #pragma unroll
;     for (int nt = 0; nt < 4; ++nt)
;       *(f32x4*)(ct + (wm * 64 + mt * 16 + l15) * 132 + wn * 64 + nt * 16 + 4 * g) = acc[mt][hf * 4 + nt];
;   __syncthreads();
; }
	v_add3_u32 v144, 0, v135, v133
	ds_read_b128 v[128:131], v144 offset:32768
	ds_read_b128 v[154:157], v144 offset:33792
	v_add3_u32 v149, 0, v134, v133
	ds_read_b128 v[132:135], v149 offset:24576
	ds_read_b128 v[136:139], v149 offset:25600
	ds_read_b128 v[140:143], v149 offset:26624
	ds_read_b128 v[150:153], v149 offset:27648
	s_waitcnt lgkmcnt(3)
	v_mfma_f32_16x16x32_bf16 v[124:127], v[128:131], v[132:135], v[124:127]
	s_waitcnt lgkmcnt(2)
	v_mfma_f32_16x16x32_bf16 v[108:111], v[128:131], v[136:139], v[108:111]
	s_waitcnt lgkmcnt(1)
	v_mfma_f32_16x16x32_bf16 v[80:83], v[128:131], v[140:143], v[80:83]
	s_waitcnt lgkmcnt(0)
	v_mfma_f32_16x16x32_bf16 v[128:131], v[128:131], v[150:153], v[36:39]
	s_nop 2
	ds_read_b128 v[36:39], v144 offset:34816
	v_mfma_f32_16x16x32_bf16 v[120:123], v[154:157], v[132:135], v[120:123]
	v_mfma_f32_16x16x32_bf16 v[100:103], v[154:157], v[136:139], v[100:103]
	v_mfma_f32_16x16x32_bf16 v[68:71], v[154:157], v[140:143], v[68:71]
	v_mfma_f32_16x16x32_bf16 v[154:157], v[154:157], v[150:153], v[24:27]
	s_nop 2
	ds_read_b128 v[24:27], v144 offset:35840
	s_waitcnt lgkmcnt(1)
	v_mfma_f32_16x16x32_bf16 v[116:119], v[36:39], v[132:135], v[116:119]
	v_mfma_f32_16x16x32_bf16 v[92:95], v[36:39], v[136:139], v[92:95]
	v_mfma_f32_16x16x32_bf16 v[158:161], v[36:39], v[140:143], v[48:51]
	v_mfma_f32_16x16x32_bf16 v[162:165], v[36:39], v[150:153], v[12:15]
	ds_read_b128 v[36:39], v144 offset:36864
	s_waitcnt lgkmcnt(1)
	v_mfma_f32_16x16x32_bf16 v[112:115], v[24:27], v[132:135], v[112:115]
	v_mfma_f32_16x16x32_bf16 v[84:87], v[24:27], v[136:139], v[84:87]
	v_mfma_f32_16x16x32_bf16 v[166:169], v[24:27], v[140:143], v[40:43]
	v_mfma_f32_16x16x32_bf16 v[170:173], v[24:27], v[150:153], v[4:7]
	s_nop 1
	ds_read_b128 v[40:43], v144 offset:37888
	s_waitcnt lgkmcnt(1)
	v_mfma_f32_16x16x32_bf16 v[24:27], v[36:39], v[132:135], v[104:107]
	v_mfma_f32_16x16x32_bf16 v[12:15], v[36:39], v[136:139], v[72:75]
	v_mfma_f32_16x16x32_bf16 v[4:7], v[36:39], v[140:143], v[28:31]
	v_mfma_f32_16x16x32_bf16 v[0:3], v[36:39], v[150:153], v[0:3]
	s_nop 0
	ds_read_b128 v[72:75], v144 offset:38912
	s_waitcnt lgkmcnt(1)
	v_mfma_f32_16x16x32_bf16 v[36:39], v[40:43], v[132:135], v[96:99]
	v_mfma_f32_16x16x32_bf16 v[28:31], v[40:43], v[136:139], v[64:67]
	v_mfma_f32_16x16x32_bf16 v[16:19], v[40:43], v[140:143], v[16:19]
	v_mfma_f32_16x16x32_bf16 v[8:11], v[40:43], v[150:153], v[8:11]
	s_nop 0
	ds_read_b128 v[64:67], v144 offset:39936
	s_waitcnt lgkmcnt(1)
	v_mfma_f32_16x16x32_bf16 v[48:51], v[72:75], v[132:135], v[88:91]
	v_mfma_f32_16x16x32_bf16 v[40:43], v[72:75], v[136:139], v[56:59]
	v_mfma_f32_16x16x32_bf16 v[32:35], v[72:75], v[140:143], v[32:35]
	v_mfma_f32_16x16x32_bf16 v[20:23], v[72:75], v[150:153], v[20:23]
	s_waitcnt lgkmcnt(0)
	v_mfma_f32_16x16x32_bf16 v[56:59], v[64:67], v[132:135], v[76:79]
	v_mfma_f32_16x16x32_bf16 v[52:55], v[64:67], v[136:139], v[52:55]
	v_mfma_f32_16x16x32_bf16 v[44:47], v[64:67], v[140:143], v[44:47]
	v_mfma_f32_16x16x32_bf16 v[60:63], v[64:67], v[150:153], v[60:63]
	v_mov_b32_e32 v200, v147
	v_mov_b32_e32 v64, v147
	s_waitcnt vmcnt(0)
	s_barrier
	s_mov_b32 s4, 0xfffffc0
	v_and_b32_e32 v66, 15, v64
	v_lshrrev_b32_e32 v67, 1, v64
	v_and_b32_e32 v65, 64, v64
	v_and_or_b32 v66, v67, s4, v66
	s_movk_i32 s4, 0x210
	v_lshl_add_u32 v65, v65, 2, 0
	v_and_b32_e32 v64, 48, v64
	v_mul_lo_u32 v66, v66, s4
	v_add3_u32 v64, v65, v64, v66
	v_and_b32_e32 v72, 31, v200
	ds_write_b128 v64, v[124:127]
	ds_write_b128 v64, v[120:123] offset:64
	ds_write_b128 v64, v[116:119] offset:128
	ds_write_b128 v64, v[112:115] offset:192
	ds_write_b128 v64, v[108:111] offset:8448
	ds_write_b128 v64, v[100:103] offset:8512
	ds_write_b128 v64, v[92:95] offset:8576
	ds_write_b128 v64, v[84:87] offset:8640
	ds_write_b128 v64, v[80:83] offset:16896
	ds_write_b128 v64, v[68:71] offset:16960
	ds_write_b128 v64, v[158:161] offset:17024
	ds_write_b128 v64, v[166:169] offset:17088
	ds_write_b128 v64, v[128:131] offset:25344
	ds_write_b128 v64, v[154:157] offset:25408
	ds_write_b128 v64, v[162:165] offset:25472
	ds_write_b128 v64, v[170:173] offset:25536
	v_mov_b32_e32 v181, v64
	v_ashrrev_i32_e32 v64, 5, v200
	v_lshl_add_u32 v144, v72, 4, 0
	v_add_u32_e32 v80, s46, v64
	v_mul_lo_u32 v64, v64, s4
	v_add_u32_e32 v149, v144, v64
	s_waitcnt lgkmcnt(0)
	s_barrier
	s_mov_b32 s6, s46
	s_mov_b32 s7, 0
	s_lshl_b64 s[4:5], s[6:7], 12
	s_add_u32 s52, s76, s4
	s_addc_u32 s53, s77, s5
	s_lshr_b64 s[4:5], s[4:5], 1
	s_add_u32 s54, s78, s4
	s_addc_u32 s55, s79, s5
	s_mov_b64 s[50:51], s[52:53]
	s_cmp_eq_u64 s[38:39], 0
	s_cbranch_scc1 .Lgoe_hdone
	v_readlane_b32 s4, v250, 21
	v_readlane_b32 s5, v250, 22
	s_cmp_lt_u32 s46, 0x10000
	s_cbranch_scc1 .Lgoe_x
	v_readlane_b32 s4, v250, 23
	v_readlane_b32 s5, v250, 24
	s_sub_i32 s6, s46, 0x10000
.Lgoe_x:
	s_lshl_b64 s[6:7], s[6:7], 12
	s_nop 0
	s_add_u32 s50, s4, s6
	s_addc_u32 s51, s5, s7
; __device__ __forceinline__ int TIDX() { int t = threadIdx.x; asm volatile("" : "+v"(t)); return t; }
; __device__ void phase_gemm_out(const Params& p, int l, unsigned char* smem, bool dry = false) {
;     ...
;     const int tid = TIDX();
; #pragma unroll
;     for (int hf = 0; hf < 2; ++hf) {
;       acc2_to_lds(acc, ct, hf);
; #pragma unroll
;       for (int i = 0; i < 16; ++i) {
;         int idx = tid + 256 * i, r = idx >> 5, c4 = idx & 31;
;         const int m = m0 + r, n = n0 + (c4 >> 4) * 128 + hf * 64 + (c4 & 15) * 4;
;         float4 x = *(const float4*)(ct + r * 132 + 4 * c4);
;         const float* hp = (l == 0) ? x_row(p, m) + n : p.out + (size_t)m * DM + n;
;         typedef float f4v __attribute__((ext_vector_type(4)));
;         const f4v hnt = __builtin_nontemporal_load((const f4v*)hp);
;         float4 hv = make_float4(hnt[0], hnt[1], hnt[2], hnt[3]);
;         float4 rr; rr.x = hv.x + x.x; rr.y = hv.y + x.y; rr.z = hv.z + x.z; rr.w = hv.w + x.w;
;         if (!dry) {
;           *(float4*)(p.out + (size_t)m * DM + n) = rr;
;           uint2 o2; o2.x = pack2(rr.x, rr.y); o2.y = pack2(rr.z, rr.w);
;           *(uint2*)(H1B + (size_t)m * DM + n) = o2;
;         }
;       }
.Lgoe_hdone:
	v_and_b32_e32 v140, 16, v200
	v_and_b32_e32 v141, 15, v200
	v_lshlrev_b32_e32 v140, 3, v140
	v_lshl_or_b32 v140, v141, 2, v140
	v_add_u32_e32 v140, s42, v140
	v_lshrrev_b32_e32 v141, 5, v200
	v_lshlrev_b32_e32 v142, 1, v140
	v_lshlrev_b32_e32 v143, 2, v140
	v_lshl_add_u32 v142, v141, 11, v142
	v_lshl_add_u32 v143, v141, 12, v143
	v_mov_b32_e32 v174, v143
	global_load_dwordx4 v[64:67], v174, s[50:51] offset:0 nt
	v_add_u32_e32 v174, 0x8000, v174
	global_load_dwordx4 v[68:71], v174, s[50:51] offset:0 nt
	v_add_u32_e32 v174, 0x8000, v174
	global_load_dwordx4 v[72:75], v174, s[50:51] offset:0 nt
	v_add_u32_e32 v174, 0x8000, v174
	global_load_dwordx4 v[76:79], v174, s[50:51] offset:0 nt
	v_add_u32_e32 v174, 0x8000, v174
	global_load_dwordx4 v[80:83], v174, s[50:51] offset:0 nt
	v_add_u32_e32 v174, 0x8000, v174
	global_load_dwordx4 v[84:87], v174, s[50:51] offset:0 nt
	v_add_u32_e32 v174, 0x8000, v174
	global_load_dwordx4 v[88:91], v174, s[50:51] offset:0 nt
	v_add_u32_e32 v174, 0x8000, v174
	global_load_dwordx4 v[92:95], v174, s[50:51] offset:0 nt
	v_add_u32_e32 v174, 0x8000, v174
	global_load_dwordx4 v[96:99], v174, s[50:51] offset:0 nt
	v_add_u32_e32 v174, 0x8000, v174
	global_load_dwordx4 v[100:103], v174, s[50:51] offset:0 nt
	v_add_u32_e32 v174, 0x8000, v174
	global_load_dwordx4 v[104:107], v174, s[50:51] offset:0 nt
	v_add_u32_e32 v174, 0x8000, v174
	global_load_dwordx4 v[108:111], v174, s[50:51] offset:0 nt
	v_add_u32_e32 v174, 0x8000, v174
	global_load_dwordx4 v[112:115], v174, s[50:51] offset:0 nt
	v_add_u32_e32 v174, 0x8000, v174
	global_load_dwordx4 v[116:119], v174, s[50:51] offset:0 nt
	v_add_u32_e32 v174, 0x8000, v174
	global_load_dwordx4 v[120:123], v174, s[50:51] offset:0 nt
	v_add_u32_e32 v174, 0x8000, v174
	global_load_dwordx4 v[124:127], v174, s[50:51] offset:0 nt
	v_mov_b32_e32 v175, v143
	v_mov_b32_e32 v176, v142
	ds_read_b128 v[128:131], v149
	ds_read_b128 v[132:135], v149 offset:4224
	ds_read_b128 v[136:139], v149 offset:8448
	s_waitcnt vmcnt(15) lgkmcnt(2)
	v_pk_add_f32 v[64:65], v[128:129], v[64:65]
	v_pk_add_f32 v[66:67], v[130:131], v[66:67]
	global_store_dwordx4 v175, v[64:67], s[52:53] offset:0
	v_cvt_pk_bf16_f32 v150, v64, v65
	v_cvt_pk_bf16_f32 v151, v66, v67
	global_store_dwordx2 v176, v[150:151], s[54:55] offset:0
	v_add_u32_e32 v175, 0x8000, v175
	v_add_u32_e32 v176, 0x4000, v176
	ds_read_b128 v[128:131], v149 offset:12672
	s_waitcnt vmcnt(16) lgkmcnt(2)
	v_pk_add_f32 v[68:69], v[132:133], v[68:69]
	v_pk_add_f32 v[70:71], v[134:135], v[70:71]
	global_store_dwordx4 v175, v[68:71], s[52:53] offset:0
	v_cvt_pk_bf16_f32 v152, v68, v69
	v_cvt_pk_bf16_f32 v153, v70, v71
	global_store_dwordx2 v176, v[152:153], s[54:55] offset:0
	v_add_u32_e32 v175, 0x8000, v175
	v_add_u32_e32 v176, 0x4000, v176
	ds_read_b128 v[132:135], v149 offset:16896
	s_waitcnt vmcnt(17) lgkmcnt(2)
	v_pk_add_f32 v[72:73], v[136:137], v[72:73]
	v_pk_add_f32 v[74:75], v[138:139], v[74:75]
	global_store_dwordx4 v175, v[72:75], s[52:53] offset:0
	v_cvt_pk_bf16_f32 v150, v72, v73
	v_cvt_pk_bf16_f32 v151, v74, v75
	global_store_dwordx2 v176, v[150:151], s[54:55] offset:0
	v_add_u32_e32 v175, 0x8000, v175
	v_add_u32_e32 v176, 0x4000, v176
	ds_read_b128 v[136:139], v149 offset:21120
	s_waitcnt vmcnt(18) lgkmcnt(2)
	v_pk_add_f32 v[76:77], v[128:129], v[76:77]
	v_pk_add_f32 v[78:79], v[130:131], v[78:79]
	global_store_dwordx4 v175, v[76:79], s[52:53] offset:0
	v_cvt_pk_bf16_f32 v152, v76, v77
	v_cvt_pk_bf16_f32 v153, v78, v79
	global_store_dwordx2 v176, v[152:153], s[54:55] offset:0
	v_add_u32_e32 v175, 0x8000, v175
	v_add_u32_e32 v176, 0x4000, v176
	ds_read_b128 v[128:131], v149 offset:25344
	s_waitcnt vmcnt(19) lgkmcnt(2)
	v_pk_add_f32 v[80:81], v[132:133], v[80:81]
	v_pk_add_f32 v[82:83], v[134:135], v[82:83]
	global_store_dwordx4 v175, v[80:83], s[52:53] offset:0
	v_cvt_pk_bf16_f32 v150, v80, v81
	v_cvt_pk_bf16_f32 v151, v82, v83
	global_store_dwordx2 v176, v[150:151], s[54:55] offset:0
	v_add_u32_e32 v175, 0x8000, v175
	v_add_u32_e32 v176, 0x4000, v176
	ds_read_b128 v[132:135], v149 offset:29568
	s_waitcnt vmcnt(20) lgkmcnt(2)
	v_pk_add_f32 v[84:85], v[136:137], v[84:85]
	v_pk_add_f32 v[86:87], v[138:139], v[86:87]
	global_store_dwordx4 v175, v[84:87], s[52:53] offset:0
	v_cvt_pk_bf16_f32 v152, v84, v85
	v_cvt_pk_bf16_f32 v153, v86, v87
	global_store_dwordx2 v176, v[152:153], s[54:55] offset:0
	v_add_u32_e32 v175, 0x8000, v175
	v_add_u32_e32 v176, 0x4000, v176
	ds_read_b128 v[136:139], v149 offset:33792
	s_waitcnt vmcnt(21) lgkmcnt(2)
	v_pk_add_f32 v[88:89], v[128:129], v[88:89]
	v_pk_add_f32 v[90:91], v[130:131], v[90:91]
	global_store_dwordx4 v175, v[88:91], s[52:53] offset:0
	v_cvt_pk_bf16_f32 v150, v88, v89
	v_cvt_pk_bf16_f32 v151, v90, v91
	global_store_dwordx2 v176, v[150:151], s[54:55] offset:0
	v_add_u32_e32 v175, 0x8000, v175
	v_add_u32_e32 v176, 0x4000, v176
	ds_read_b128 v[128:131], v149 offset:38016
	s_waitcnt vmcnt(22) lgkmcnt(2)
	v_pk_add_f32 v[92:93], v[132:133], v[92:93]
	v_pk_add_f32 v[94:95], v[134:135], v[94:95]
	global_store_dwordx4 v175, v[92:95], s[52:53] offset:0
	v_cvt_pk_bf16_f32 v152, v92, v93
	v_cvt_pk_bf16_f32 v153, v94, v95
	global_store_dwordx2 v176, v[152:153], s[54:55] offset:0
	v_add_u32_e32 v175, 0x8000, v175
	v_add_u32_e32 v176, 0x4000, v176
	ds_read_b128 v[132:135], v149 offset:42240
	s_waitcnt vmcnt(23) lgkmcnt(2)
	v_pk_add_f32 v[96:97], v[136:137], v[96:97]
	v_pk_add_f32 v[98:99], v[138:139], v[98:99]
	global_store_dwordx4 v175, v[96:99], s[52:53] offset:0
	v_cvt_pk_bf16_f32 v150, v96, v97
	v_cvt_pk_bf16_f32 v151, v98, v99
	global_store_dwordx2 v176, v[150:151], s[54:55] offset:0
	v_add_u32_e32 v175, 0x8000, v175
	v_add_u32_e32 v176, 0x4000, v176
	ds_read_b128 v[136:139], v149 offset:46464
	s_waitcnt vmcnt(24) lgkmcnt(2)
; __device__ __forceinline__ int TIDX() { int t = threadIdx.x; asm volatile("" : "+v"(t)); return t; }
; __device__ __forceinline__ void acc2_to_lds(const f32x4 (&acc)[4][8], float* ct, int hf) {
;   const int tid = TIDX(), lane = tid & 63, w = tid >> 6, wm = w >> 1, wn = w & 1, l15 = lane & 15, g = lane >> 4;
; #pragma unroll
;   for (int mt = 0; mt < 4; ++mt)
; #pragma unroll
;     for (int nt = 0; nt < 4; ++nt)
;       *(f32x4*)(ct + (wm * 64 + mt * 16 + l15) * 132 + wn * 64 + nt * 16 + 4 * g) = acc[mt][hf * 4 + nt];
;   __syncthreads();
; }
; __device__ void phase_gemm_out(const Params& p, int l, unsigned char* smem, bool dry = false) {
;     ...
; #pragma unroll
;     for (int hf = 0; hf < 2; ++hf) {
;       acc2_to_lds(acc, ct, hf);
; #pragma unroll
;       for (int i = 0; i < 16; ++i) {
;         int idx = tid + 256 * i, r = idx >> 5, c4 = idx & 31;
;         const int m = m0 + r, n = n0 + (c4 >> 4) * 128 + hf * 64 + (c4 & 15) * 4;
;         float4 x = *(const float4*)(ct + r * 132 + 4 * c4);
;         const float* hp = (l == 0) ? x_row(p, m) + n : p.out + (size_t)m * DM + n;
;         typedef float f4v __attribute__((ext_vector_type(4)));
;         const f4v hnt = __builtin_nontemporal_load((const f4v*)hp);
;         float4 hv = make_float4(hnt[0], hnt[1], hnt[2], hnt[3]);
;         float4 rr; rr.x = hv.x + x.x; rr.y = hv.y + x.y; rr.z = hv.z + x.z; rr.w = hv.w + x.w;
;         if (!dry) {
;           *(float4*)(p.out + (size_t)m * DM + n) = rr;
;           uint2 o2; o2.x = pack2(rr.x, rr.y); o2.y = pack2(rr.z, rr.w);
;           *(uint2*)(H1B + (size_t)m * DM + n) = o2;
;         }
;       }
;       __syncthreads();
	v_pk_add_f32 v[100:101], v[128:129], v[100:101]
	v_pk_add_f32 v[102:103], v[130:131], v[102:103]
	global_store_dwordx4 v175, v[100:103], s[52:53] offset:0
	v_cvt_pk_bf16_f32 v152, v100, v101
	v_cvt_pk_bf16_f32 v153, v102, v103
	global_store_dwordx2 v176, v[152:153], s[54:55] offset:0
	v_add_u32_e32 v175, 0x8000, v175
	v_add_u32_e32 v176, 0x4000, v176
	ds_read_b128 v[128:131], v149 offset:50688
	s_waitcnt vmcnt(25) lgkmcnt(2)
	v_pk_add_f32 v[104:105], v[132:133], v[104:105]
	v_pk_add_f32 v[106:107], v[134:135], v[106:107]
	global_store_dwordx4 v175, v[104:107], s[52:53] offset:0
	v_cvt_pk_bf16_f32 v150, v104, v105
	v_cvt_pk_bf16_f32 v151, v106, v107
	global_store_dwordx2 v176, v[150:151], s[54:55] offset:0
	v_add_u32_e32 v175, 0x8000, v175
	v_add_u32_e32 v176, 0x4000, v176
	ds_read_b128 v[132:135], v149 offset:54912
	s_waitcnt vmcnt(26) lgkmcnt(2)
	v_pk_add_f32 v[108:109], v[136:137], v[108:109]
	v_pk_add_f32 v[110:111], v[138:139], v[110:111]
	global_store_dwordx4 v175, v[108:111], s[52:53] offset:0
	v_cvt_pk_bf16_f32 v152, v108, v109
	v_cvt_pk_bf16_f32 v153, v110, v111
	global_store_dwordx2 v176, v[152:153], s[54:55] offset:0
	v_add_u32_e32 v175, 0x8000, v175
	v_add_u32_e32 v176, 0x4000, v176
	ds_read_b128 v[136:139], v149 offset:59136
	s_waitcnt vmcnt(27) lgkmcnt(2)
	v_pk_add_f32 v[112:113], v[128:129], v[112:113]
	v_pk_add_f32 v[114:115], v[130:131], v[114:115]
	global_store_dwordx4 v175, v[112:115], s[52:53] offset:0
	v_cvt_pk_bf16_f32 v150, v112, v113
	v_cvt_pk_bf16_f32 v151, v114, v115
	global_store_dwordx2 v176, v[150:151], s[54:55] offset:0
	v_add_u32_e32 v175, 0x8000, v175
	v_add_u32_e32 v176, 0x4000, v176
	ds_read_b128 v[128:131], v149 offset:63360
	s_waitcnt vmcnt(28) lgkmcnt(2)
	v_pk_add_f32 v[116:117], v[132:133], v[116:117]
	v_pk_add_f32 v[118:119], v[134:135], v[118:119]
	global_store_dwordx4 v175, v[116:119], s[52:53] offset:0
	v_cvt_pk_bf16_f32 v152, v116, v117
	v_cvt_pk_bf16_f32 v153, v118, v119
	global_store_dwordx2 v176, v[152:153], s[54:55] offset:0
	v_add_u32_e32 v175, 0x8000, v175
	v_add_u32_e32 v176, 0x4000, v176
	s_waitcnt vmcnt(29) lgkmcnt(1)
	v_pk_add_f32 v[120:121], v[136:137], v[120:121]
	v_pk_add_f32 v[122:123], v[138:139], v[122:123]
	global_store_dwordx4 v175, v[120:123], s[52:53] offset:0
	v_cvt_pk_bf16_f32 v150, v120, v121
	v_cvt_pk_bf16_f32 v151, v122, v123
	global_store_dwordx2 v176, v[150:151], s[54:55] offset:0
	v_add_u32_e32 v175, 0x8000, v175
	v_add_u32_e32 v176, 0x4000, v176
	s_waitcnt vmcnt(30) lgkmcnt(0)
	v_pk_add_f32 v[124:125], v[128:129], v[124:125]
	v_pk_add_f32 v[126:127], v[130:131], v[126:127]
	global_store_dwordx4 v175, v[124:127], s[52:53] offset:0
	v_cvt_pk_bf16_f32 v152, v124, v125
	v_cvt_pk_bf16_f32 v153, v126, v127
	global_store_dwordx2 v176, v[152:153], s[54:55] offset:0
	s_barrier
	ds_write_b128 v181, v[24:27]
	ds_write_b128 v181, v[36:39] offset:64
	ds_write_b128 v181, v[48:51] offset:128
	ds_write_b128 v181, v[56:59] offset:192
	ds_write_b128 v181, v[12:15] offset:8448
	ds_write_b128 v181, v[28:31] offset:8512
	ds_write_b128 v181, v[40:43] offset:8576
	ds_write_b128 v181, v[52:55] offset:8640
	ds_write_b128 v181, v[4:7] offset:16896
	ds_write_b128 v181, v[16:19] offset:16960
	ds_write_b128 v181, v[32:35] offset:17024
	ds_write_b128 v181, v[44:47] offset:17088
	ds_write_b128 v181, v[0:3] offset:25344
	ds_write_b128 v181, v[8:11] offset:25408
	ds_write_b128 v181, v[20:23] offset:25472
	ds_write_b128 v181, v[60:63] offset:25536
	s_waitcnt lgkmcnt(0)
	s_barrier
	v_mov_b32_e32 v174, v143
	global_load_dwordx4 v[64:67], v174, s[50:51] offset:256 nt
	v_add_u32_e32 v174, 0x8000, v174
	global_load_dwordx4 v[68:71], v174, s[50:51] offset:256 nt
	v_add_u32_e32 v174, 0x8000, v174
	global_load_dwordx4 v[72:75], v174, s[50:51] offset:256 nt
	v_add_u32_e32 v174, 0x8000, v174
	global_load_dwordx4 v[76:79], v174, s[50:51] offset:256 nt
	v_add_u32_e32 v174, 0x8000, v174
	global_load_dwordx4 v[80:83], v174, s[50:51] offset:256 nt
	v_add_u32_e32 v174, 0x8000, v174
	global_load_dwordx4 v[84:87], v174, s[50:51] offset:256 nt
	v_add_u32_e32 v174, 0x8000, v174
	global_load_dwordx4 v[88:91], v174, s[50:51] offset:256 nt
	v_add_u32_e32 v174, 0x8000, v174
	global_load_dwordx4 v[92:95], v174, s[50:51] offset:256 nt
	v_add_u32_e32 v174, 0x8000, v174
	global_load_dwordx4 v[96:99], v174, s[50:51] offset:256 nt
	v_add_u32_e32 v174, 0x8000, v174
	global_load_dwordx4 v[100:103], v174, s[50:51] offset:256 nt
	v_add_u32_e32 v174, 0x8000, v174
	global_load_dwordx4 v[104:107], v174, s[50:51] offset:256 nt
	v_add_u32_e32 v174, 0x8000, v174
	global_load_dwordx4 v[108:111], v174, s[50:51] offset:256 nt
	v_add_u32_e32 v174, 0x8000, v174
	global_load_dwordx4 v[112:115], v174, s[50:51] offset:256 nt
	v_add_u32_e32 v174, 0x8000, v174
	global_load_dwordx4 v[116:119], v174, s[50:51] offset:256 nt
	v_add_u32_e32 v174, 0x8000, v174
	global_load_dwordx4 v[120:123], v174, s[50:51] offset:256 nt
	v_add_u32_e32 v174, 0x8000, v174
	global_load_dwordx4 v[124:127], v174, s[50:51] offset:256 nt
	v_mov_b32_e32 v175, v143
	v_mov_b32_e32 v176, v142
	ds_read_b128 v[128:131], v149
	ds_read_b128 v[132:135], v149 offset:4224
	ds_read_b128 v[136:139], v149 offset:8448
	s_waitcnt vmcnt(15) lgkmcnt(2)
	v_pk_add_f32 v[64:65], v[128:129], v[64:65]
	v_pk_add_f32 v[66:67], v[130:131], v[66:67]
	global_store_dwordx4 v175, v[64:67], s[52:53] offset:256
	v_cvt_pk_bf16_f32 v150, v64, v65
	v_cvt_pk_bf16_f32 v151, v66, v67
	global_store_dwordx2 v176, v[150:151], s[54:55] offset:128
	v_add_u32_e32 v175, 0x8000, v175
	v_add_u32_e32 v176, 0x4000, v176
	ds_read_b128 v[128:131], v149 offset:12672
	s_waitcnt vmcnt(16) lgkmcnt(2)
; __device__ void phase_gemm_out(const Params& p, int l, unsigned char* smem, bool dry = false) {
;     ...
;   for (int v = it.v; v < it.end; v += it.step) {
;     ...
; #pragma unroll
;       for (int i = 0; i < 16; ++i) {
;         int idx = tid + 256 * i, r = idx >> 5, c4 = idx & 31;
;         const int m = m0 + r, n = n0 + (c4 >> 4) * 128 + hf * 64 + (c4 & 15) * 4;
;         float4 x = *(const float4*)(ct + r * 132 + 4 * c4);
;         const float* hp = (l == 0) ? x_row(p, m) + n : p.out + (size_t)m * DM + n;
;         typedef float f4v __attribute__((ext_vector_type(4)));
;         const f4v hnt = __builtin_nontemporal_load((const f4v*)hp);
;         float4 hv = make_float4(hnt[0], hnt[1], hnt[2], hnt[3]);
;         float4 rr; rr.x = hv.x + x.x; rr.y = hv.y + x.y; rr.z = hv.z + x.z; rr.w = hv.w + x.w;
;         if (!dry) {
;           *(float4*)(p.out + (size_t)m * DM + n) = rr;
;           uint2 o2; o2.x = pack2(rr.x, rr.y); o2.y = pack2(rr.z, rr.w);
;           *(uint2*)(H1B + (size_t)m * DM + n) = o2;
;         }
;       }
;       __syncthreads();
	v_pk_add_f32 v[68:69], v[132:133], v[68:69]
	v_pk_add_f32 v[70:71], v[134:135], v[70:71]
	global_store_dwordx4 v175, v[68:71], s[52:53] offset:256
	v_cvt_pk_bf16_f32 v152, v68, v69
	v_cvt_pk_bf16_f32 v153, v70, v71
	global_store_dwordx2 v176, v[152:153], s[54:55] offset:128
	v_add_u32_e32 v175, 0x8000, v175
	v_add_u32_e32 v176, 0x4000, v176
	ds_read_b128 v[132:135], v149 offset:16896
	s_waitcnt vmcnt(17) lgkmcnt(2)
	v_pk_add_f32 v[72:73], v[136:137], v[72:73]
	v_pk_add_f32 v[74:75], v[138:139], v[74:75]
	global_store_dwordx4 v175, v[72:75], s[52:53] offset:256
	v_cvt_pk_bf16_f32 v150, v72, v73
	v_cvt_pk_bf16_f32 v151, v74, v75
	global_store_dwordx2 v176, v[150:151], s[54:55] offset:128
	v_add_u32_e32 v175, 0x8000, v175
	v_add_u32_e32 v176, 0x4000, v176
	ds_read_b128 v[136:139], v149 offset:21120
	s_waitcnt vmcnt(18) lgkmcnt(2)
	v_pk_add_f32 v[76:77], v[128:129], v[76:77]
	v_pk_add_f32 v[78:79], v[130:131], v[78:79]
	global_store_dwordx4 v175, v[76:79], s[52:53] offset:256
	v_cvt_pk_bf16_f32 v152, v76, v77
	v_cvt_pk_bf16_f32 v153, v78, v79
	global_store_dwordx2 v176, v[152:153], s[54:55] offset:128
	v_add_u32_e32 v175, 0x8000, v175
	v_add_u32_e32 v176, 0x4000, v176
	ds_read_b128 v[128:131], v149 offset:25344
	s_waitcnt vmcnt(19) lgkmcnt(2)
	v_pk_add_f32 v[80:81], v[132:133], v[80:81]
	v_pk_add_f32 v[82:83], v[134:135], v[82:83]
	global_store_dwordx4 v175, v[80:83], s[52:53] offset:256
	v_cvt_pk_bf16_f32 v150, v80, v81
	v_cvt_pk_bf16_f32 v151, v82, v83
	global_store_dwordx2 v176, v[150:151], s[54:55] offset:128
	v_add_u32_e32 v175, 0x8000, v175
	v_add_u32_e32 v176, 0x4000, v176
	ds_read_b128 v[132:135], v149 offset:29568
	s_waitcnt vmcnt(20) lgkmcnt(2)
	v_pk_add_f32 v[84:85], v[136:137], v[84:85]
	v_pk_add_f32 v[86:87], v[138:139], v[86:87]
	global_store_dwordx4 v175, v[84:87], s[52:53] offset:256
	v_cvt_pk_bf16_f32 v152, v84, v85
	v_cvt_pk_bf16_f32 v153, v86, v87
	global_store_dwordx2 v176, v[152:153], s[54:55] offset:128
	v_add_u32_e32 v175, 0x8000, v175
	v_add_u32_e32 v176, 0x4000, v176
	ds_read_b128 v[136:139], v149 offset:33792
	s_waitcnt vmcnt(21) lgkmcnt(2)
	v_pk_add_f32 v[88:89], v[128:129], v[88:89]
	v_pk_add_f32 v[90:91], v[130:131], v[90:91]
	global_store_dwordx4 v175, v[88:91], s[52:53] offset:256
	v_cvt_pk_bf16_f32 v150, v88, v89
	v_cvt_pk_bf16_f32 v151, v90, v91
	global_store_dwordx2 v176, v[150:151], s[54:55] offset:128
	v_add_u32_e32 v175, 0x8000, v175
	v_add_u32_e32 v176, 0x4000, v176
	ds_read_b128 v[128:131], v149 offset:38016
	s_waitcnt vmcnt(22) lgkmcnt(2)
	v_pk_add_f32 v[92:93], v[132:133], v[92:93]
	v_pk_add_f32 v[94:95], v[134:135], v[94:95]
	global_store_dwordx4 v175, v[92:95], s[52:53] offset:256
	v_cvt_pk_bf16_f32 v152, v92, v93
	v_cvt_pk_bf16_f32 v153, v94, v95
	global_store_dwordx2 v176, v[152:153], s[54:55] offset:128
	v_add_u32_e32 v175, 0x8000, v175
	v_add_u32_e32 v176, 0x4000, v176
	ds_read_b128 v[132:135], v149 offset:42240
	s_waitcnt vmcnt(23) lgkmcnt(2)
	v_pk_add_f32 v[96:97], v[136:137], v[96:97]
	v_pk_add_f32 v[98:99], v[138:139], v[98:99]
	global_store_dwordx4 v175, v[96:99], s[52:53] offset:256
	v_cvt_pk_bf16_f32 v150, v96, v97
	v_cvt_pk_bf16_f32 v151, v98, v99
	global_store_dwordx2 v176, v[150:151], s[54:55] offset:128
	v_add_u32_e32 v175, 0x8000, v175
	v_add_u32_e32 v176, 0x4000, v176
	ds_read_b128 v[136:139], v149 offset:46464
	s_waitcnt vmcnt(24) lgkmcnt(2)
	v_pk_add_f32 v[100:101], v[128:129], v[100:101]
	v_pk_add_f32 v[102:103], v[130:131], v[102:103]
	global_store_dwordx4 v175, v[100:103], s[52:53] offset:256
	v_cvt_pk_bf16_f32 v152, v100, v101
	v_cvt_pk_bf16_f32 v153, v102, v103
	global_store_dwordx2 v176, v[152:153], s[54:55] offset:128
	v_add_u32_e32 v175, 0x8000, v175
	v_add_u32_e32 v176, 0x4000, v176
	ds_read_b128 v[128:131], v149 offset:50688
	s_waitcnt vmcnt(25) lgkmcnt(2)
	v_pk_add_f32 v[104:105], v[132:133], v[104:105]
	v_pk_add_f32 v[106:107], v[134:135], v[106:107]
	global_store_dwordx4 v175, v[104:107], s[52:53] offset:256
	v_cvt_pk_bf16_f32 v150, v104, v105
	v_cvt_pk_bf16_f32 v151, v106, v107
	global_store_dwordx2 v176, v[150:151], s[54:55] offset:128
	v_add_u32_e32 v175, 0x8000, v175
	v_add_u32_e32 v176, 0x4000, v176
	ds_read_b128 v[132:135], v149 offset:54912
	s_waitcnt vmcnt(26) lgkmcnt(2)
	v_pk_add_f32 v[108:109], v[136:137], v[108:109]
	v_pk_add_f32 v[110:111], v[138:139], v[110:111]
	global_store_dwordx4 v175, v[108:111], s[52:53] offset:256
	v_cvt_pk_bf16_f32 v152, v108, v109
	v_cvt_pk_bf16_f32 v153, v110, v111
	global_store_dwordx2 v176, v[152:153], s[54:55] offset:128
	v_add_u32_e32 v175, 0x8000, v175
	v_add_u32_e32 v176, 0x4000, v176
	ds_read_b128 v[136:139], v149 offset:59136
	s_waitcnt vmcnt(27) lgkmcnt(2)
	v_pk_add_f32 v[112:113], v[128:129], v[112:113]
	v_pk_add_f32 v[114:115], v[130:131], v[114:115]
	global_store_dwordx4 v175, v[112:115], s[52:53] offset:256
	v_cvt_pk_bf16_f32 v150, v112, v113
	v_cvt_pk_bf16_f32 v151, v114, v115
	global_store_dwordx2 v176, v[150:151], s[54:55] offset:128
	v_add_u32_e32 v175, 0x8000, v175
	v_add_u32_e32 v176, 0x4000, v176
	ds_read_b128 v[128:131], v149 offset:63360
	s_waitcnt vmcnt(28) lgkmcnt(2)
	v_pk_add_f32 v[116:117], v[132:133], v[116:117]
	v_pk_add_f32 v[118:119], v[134:135], v[118:119]
	global_store_dwordx4 v175, v[116:119], s[52:53] offset:256
	v_cvt_pk_bf16_f32 v152, v116, v117
	v_cvt_pk_bf16_f32 v153, v118, v119
	global_store_dwordx2 v176, v[152:153], s[54:55] offset:128
	v_add_u32_e32 v175, 0x8000, v175
	v_add_u32_e32 v176, 0x4000, v176
	s_waitcnt vmcnt(29) lgkmcnt(1)
	v_pk_add_f32 v[120:121], v[136:137], v[120:121]
	v_pk_add_f32 v[122:123], v[138:139], v[122:123]
	global_store_dwordx4 v175, v[120:123], s[52:53] offset:256
	v_cvt_pk_bf16_f32 v150, v120, v121
	v_cvt_pk_bf16_f32 v151, v122, v123
	global_store_dwordx2 v176, v[150:151], s[54:55] offset:128
	v_add_u32_e32 v175, 0x8000, v175
	v_add_u32_e32 v176, 0x4000, v176
	s_waitcnt vmcnt(30) lgkmcnt(0)
	v_pk_add_f32 v[124:125], v[128:129], v[124:125]
	v_pk_add_f32 v[126:127], v[130:131], v[126:127]
	global_store_dwordx4 v175, v[124:127], s[52:53] offset:256
	v_cvt_pk_bf16_f32 v152, v124, v125
	v_cvt_pk_bf16_f32 v153, v126, v127
	global_store_dwordx2 v176, v[152:153], s[54:55] offset:128
	s_add_i32 s36, s36, s49
	s_cmp_ge_i32 s36, s48
	s_barrier
	s_cbranch_scc1 .LBB0_184
	s_branch .LBB0_118

; __device__ void transpose_tile(const float* __restrict__ src, u16* __restrict__ dst, int K, int N, int tile, float* sm) {
;     ...
;   __syncthreads();
; #pragma unroll
;   for (int i = 0; i < 16; ++i) {
;     int k = (tid >> 6) + 4 * i, n = tid & 63;
;     sm[k * 65 + n] = src[(size_t)(k0 + k) * N + n0 + n];
;   }
;   __syncthreads();
; __device__ void phase_prep(const Params& p, unsigned char* smem) {
;     ...
;     else if (r < 1088) transpose_tile(p.w_out + (size_t)l * DM * DM, p.WOUT + (size_t)l * DM * DM, DM, DM, r - 832, sm);
.LBB0_424:
	s_andn2_b64 vcc, exec, s[42:43]
	s_cbranch_vccnz .LBB0_426
	v_readlane_b32 s4, v250, 21
	s_lshl_b64 s[40:41], s[38:39], 2
	v_readlane_b32 s16, v250, 33
	v_readlane_b32 s5, v250, 22
	v_readlane_b32 s6, v250, 23
	v_readlane_b32 s7, v250, 24
	v_readlane_b32 s8, v250, 25
	v_readlane_b32 s9, v250, 26
	v_readlane_b32 s10, v250, 27
	v_readlane_b32 s11, v250, 28
	v_readlane_b32 s12, v250, 29
	v_readlane_b32 s13, v250, 30
	v_readlane_b32 s14, v250, 31
	v_readlane_b32 s15, v250, 32
	v_readlane_b32 s17, v250, 34
	v_readlane_b32 s18, v250, 35
	v_readlane_b32 s19, v250, 36
	s_add_u32 s42, s16, s40
	s_addc_u32 s43, s17, s41
	s_lshl_b64 s[40:41], s[38:39], 1
	v_readlane_b32 s4, v250, 5
	v_readlane_b32 s5, v250, 6
	s_add_u32 s39, s4, s40
	s_addc_u32 s38, s5, s41
	s_lshl_b32 s31, s30, 9
	v_mov_b32_e32 v0, v147
	s_sub_i32 s31, s45, s31
	s_and_b32 s47, s31, 0x3c0
	s_and_b32 s31, s44, 0x3c0
	v_ashrrev_i32_e32 v18, 6, v0
	s_lshl_b32 s40, s31, 2
	v_add_u32_e32 v20, 4, v18
	v_add_u32_e32 v21, 8, v18
	v_add_u32_e32 v22, 12, v18
	v_add_u32_e32 v23, 16, v18
	v_add_u32_e32 v24, 20, v18
	v_add_u32_e32 v25, 24, v18
	v_add_u32_e32 v26, 28, v18
	v_and_b32_e32 v19, 63, v0
	s_add_u32 s40, s42, s40
	v_add_u32_e32 v2, s47, v18
	v_add_u32_e32 v4, s47, v20
	v_add_u32_e32 v6, s47, v21
	v_add_u32_e32 v8, s47, v22
	v_add_u32_e32 v10, s47, v23
	v_add_u32_e32 v12, s47, v24
	v_add_u32_e32 v14, s47, v25
	v_add_u32_e32 v16, s47, v26
	s_addc_u32 s41, s43, 0
	v_lshlrev_b32_e32 v144, 2, v19
	v_ashrrev_i32_e32 v3, 31, v2
	v_ashrrev_i32_e32 v5, 31, v4
	v_ashrrev_i32_e32 v7, 31, v6
	v_ashrrev_i32_e32 v9, 31, v8
	v_ashrrev_i32_e32 v11, 31, v10
	v_ashrrev_i32_e32 v13, 31, v12
	v_ashrrev_i32_e32 v15, 31, v14
	v_ashrrev_i32_e32 v17, 31, v16
	v_lshl_add_u64 v[0:1], s[40:41], 0, v[144:145]
	v_lshlrev_b64 v[2:3], 12, v[2:3]
	v_lshlrev_b64 v[4:5], 12, v[4:5]
	v_lshlrev_b64 v[6:7], 12, v[6:7]
	v_lshlrev_b64 v[8:9], 12, v[8:9]
	v_lshlrev_b64 v[10:11], 12, v[10:11]
	v_lshlrev_b64 v[12:13], 12, v[12:13]
	v_lshlrev_b64 v[14:15], 12, v[14:15]
	v_lshlrev_b64 v[16:17], 12, v[16:17]
	v_lshl_add_u64 v[2:3], v[0:1], 0, v[2:3]
	v_lshl_add_u64 v[4:5], v[0:1], 0, v[4:5]
	v_lshl_add_u64 v[6:7], v[0:1], 0, v[6:7]
	v_lshl_add_u64 v[8:9], v[0:1], 0, v[8:9]
	v_lshl_add_u64 v[10:11], v[0:1], 0, v[10:11]
	v_lshl_add_u64 v[12:13], v[0:1], 0, v[12:13]
	v_lshl_add_u64 v[14:15], v[0:1], 0, v[14:15]
	v_lshl_add_u64 v[16:17], v[0:1], 0, v[16:17]
	v_add_u32_e32 v35, 32, v18
	v_add_u32_e32 v36, 36, v18
	v_add_u32_e32 v37, 40, v18
	v_add_u32_e32 v38, 44, v18
	v_add_u32_e32 v39, 48, v18
	v_add_u32_e32 v40, 52, v18
	v_add_u32_e32 v41, 56, v18
	v_add_u32_e32 v42, 60, v18
	s_barrier
	global_load_dword v27, v[2:3], off
	global_load_dword v28, v[4:5], off
	global_load_dword v29, v[6:7], off
	global_load_dword v30, v[8:9], off
	global_load_dword v31, v[10:11], off
	global_load_dword v32, v[12:13], off
	global_load_dword v33, v[14:15], off
	global_load_dword v34, v[16:17], off
	v_add_u32_e32 v2, s47, v35
	v_add_u32_e32 v4, s47, v36
	v_add_u32_e32 v6, s47, v37
	v_add_u32_e32 v8, s47, v38
	v_add_u32_e32 v10, s47, v39
	v_add_u32_e32 v12, s47, v40
	v_add_u32_e32 v14, s47, v41
	v_add_u32_e32 v16, s47, v42
	v_ashrrev_i32_e32 v3, 31, v2
	v_ashrrev_i32_e32 v5, 31, v4
	v_ashrrev_i32_e32 v7, 31, v6
	v_ashrrev_i32_e32 v9, 31, v8
	v_ashrrev_i32_e32 v11, 31, v10
	v_ashrrev_i32_e32 v13, 31, v12
	v_ashrrev_i32_e32 v15, 31, v14
	v_ashrrev_i32_e32 v17, 31, v16
	v_lshlrev_b64 v[2:3], 12, v[2:3]
	v_lshlrev_b64 v[4:5], 12, v[4:5]
	v_lshlrev_b64 v[6:7], 12, v[6:7]
	v_lshlrev_b64 v[8:9], 12, v[8:9]
	v_lshlrev_b64 v[10:11], 12, v[10:11]
	v_lshlrev_b64 v[12:13], 12, v[12:13]
	v_lshlrev_b64 v[14:15], 12, v[14:15]
	v_lshlrev_b64 v[16:17], 12, v[16:17]
	v_lshl_add_u64 v[2:3], v[0:1], 0, v[2:3]
	v_lshl_add_u64 v[4:5], v[0:1], 0, v[4:5]
	v_lshl_add_u64 v[6:7], v[0:1], 0, v[6:7]
	v_lshl_add_u64 v[8:9], v[0:1], 0, v[8:9]
	v_lshl_add_u64 v[10:11], v[0:1], 0, v[10:11]
	v_lshl_add_u64 v[12:13], v[0:1], 0, v[12:13]
	v_lshl_add_u64 v[14:15], v[0:1], 0, v[14:15]
	v_lshl_add_u64 v[0:1], v[0:1], 0, v[16:17]
	global_load_dword v2, v[2:3], off
	s_nop 0
	global_load_dword v3, v[4:5], off
	s_nop 0
	global_load_dword v4, v[6:7], off
	global_load_dword v5, v[8:9], off
	s_nop 0
	global_load_dword v6, v[10:11], off
	global_load_dword v7, v[12:13], off
	global_load_dword v8, v[14:15], off
	s_nop 0
	global_load_dword v0, v[0:1], off
	s_movk_i32 s4, 0x104
	v_mul_lo_u32 v1, v18, s4
	v_add3_u32 v1, 0, v144, v1
	s_waitcnt vmcnt(15)
	ds_write_b32 v1, v27
	s_waitcnt vmcnt(14)
	ds_write_b32 v1, v28 offset:1040
	s_waitcnt vmcnt(13)
	ds_write_b32 v1, v29 offset:2080
	s_waitcnt vmcnt(12)
	ds_write_b32 v1, v30 offset:3120
	s_waitcnt vmcnt(11)
	ds_write_b32 v1, v31 offset:4160
	s_waitcnt vmcnt(10)
	ds_write_b32 v1, v32 offset:5200
	s_waitcnt vmcnt(9)
	ds_write_b32 v1, v33 offset:6240
	s_waitcnt vmcnt(8)
	ds_write_b32 v1, v34 offset:7280
	s_waitcnt vmcnt(7)
	ds_write_b32 v1, v2 offset:8320
	s_waitcnt vmcnt(6)
	ds_write_b32 v1, v3 offset:9360
	s_waitcnt vmcnt(5)
	ds_write_b32 v1, v4 offset:10400
	s_waitcnt vmcnt(4)
	ds_write_b32 v1, v5 offset:11440
	s_waitcnt vmcnt(3)
	ds_write_b32 v1, v6 offset:12480
	s_waitcnt vmcnt(2)
	ds_write_b32 v1, v7 offset:13520
	s_waitcnt vmcnt(1)
	ds_write_b32 v1, v8 offset:14560
	s_waitcnt vmcnt(0)
	ds_write_b32 v1, v0 offset:15600
	v_mul_u32_u24_e32 v0, 0x104, v19
	v_lshlrev_b32_e32 v1, 2, v18
	v_add3_u32 v8, 0, v0, v1
	s_waitcnt lgkmcnt(0)
	s_barrier
; __device__ void transpose_tile(const float* __restrict__ src, u16* __restrict__ dst, int K, int N, int tile, float* sm) {
;     ...
; #pragma unroll
;   for (int i = 0; i < 16; ++i) {
;     int n = (tid >> 6) + 4 * i, k = tid & 63;
;     dst[(size_t)(n0 + n) * K + k0 + k] = (u16)f2bf(sm[k * 65 + n]);
;   }
; __device__ void phase_prep(const Params& p, unsigned char* smem) {
;     ...
;     else if (r < 1088) transpose_tile(p.w_out + (size_t)l * DM * DM, p.WOUT + (size_t)l * DM * DM, DM, DM, r - 832, sm);
	ds_read2_b32 v[2:3], v8 offset1:4
	s_lshl_b32 s40, s47, 11
	s_add_u32 s40, s39, s40
	v_add_u32_e32 v6, s31, v18
	s_addc_u32 s41, s38, 0
	v_and_b32_e32 v144, 31, v19
	v_lshrrev_b32_e32 v9, 5, v19
	v_lshlrev_b32_e32 v144, 1, v144
	s_mov_b32 s4, 0x10000
	v_mad_u32_u24 v144, v9, s4, v144
	v_ashrrev_i32_e32 v7, 31, v6
	v_lshl_add_u64 v[0:1], s[40:41], 0, v[144:145]
	v_lshlrev_b64 v[6:7], 6, v[6:7]
	s_waitcnt lgkmcnt(0)
	v_cvt_pk_bf16_f32 v2, v2, s0
	v_lshl_add_u64 v[6:7], v[0:1], 0, v[6:7]
	global_store_short v[6:7], v2, off
	v_add_u32_e32 v2, s31, v20
	v_cvt_pk_bf16_f32 v6, v3, s0
	v_ashrrev_i32_e32 v3, 31, v2
	ds_read2_b32 v[4:5], v8 offset0:8 offset1:12
	v_lshlrev_b64 v[2:3], 6, v[2:3]
	v_lshl_add_u64 v[2:3], v[0:1], 0, v[2:3]
	global_store_short v[2:3], v6, off
	v_add_u32_e32 v2, s31, v21
	v_ashrrev_i32_e32 v3, 31, v2
	v_lshlrev_b64 v[2:3], 6, v[2:3]
	s_waitcnt lgkmcnt(0)
	v_cvt_pk_bf16_f32 v4, v4, s0
	v_lshl_add_u64 v[2:3], v[0:1], 0, v[2:3]
	global_store_short v[2:3], v4, off
	v_add_u32_e32 v2, s31, v22
	v_ashrrev_i32_e32 v3, 31, v2
	v_cvt_pk_bf16_f32 v6, v5, s0
	ds_read2_b32 v[4:5], v8 offset0:16 offset1:20
	v_lshlrev_b64 v[2:3], 6, v[2:3]
	v_lshl_add_u64 v[2:3], v[0:1], 0, v[2:3]
	global_store_short v[2:3], v6, off
	v_add_u32_e32 v2, s31, v23
	v_ashrrev_i32_e32 v3, 31, v2
	v_lshlrev_b64 v[2:3], 6, v[2:3]
	s_waitcnt lgkmcnt(0)
	v_cvt_pk_bf16_f32 v4, v4, s0
	v_lshl_add_u64 v[2:3], v[0:1], 0, v[2:3]
	global_store_short v[2:3], v4, off
	v_add_u32_e32 v2, s31, v24
	v_ashrrev_i32_e32 v3, 31, v2
	v_cvt_pk_bf16_f32 v6, v5, s0
	ds_read2_b32 v[4:5], v8 offset0:24 offset1:28
	v_lshlrev_b64 v[2:3], 6, v[2:3]
	v_lshl_add_u64 v[2:3], v[0:1], 0, v[2:3]
	global_store_short v[2:3], v6, off
	v_add_u32_e32 v2, s31, v25
	v_ashrrev_i32_e32 v3, 31, v2
	v_lshlrev_b64 v[2:3], 6, v[2:3]
	s_waitcnt lgkmcnt(0)
	v_cvt_pk_bf16_f32 v4, v4, s0
	v_lshl_add_u64 v[2:3], v[0:1], 0, v[2:3]
	global_store_short v[2:3], v4, off
	v_add_u32_e32 v2, s31, v26
	v_ashrrev_i32_e32 v3, 31, v2
	v_cvt_pk_bf16_f32 v6, v5, s0
	ds_read2_b32 v[4:5], v8 offset0:32 offset1:36
	v_lshlrev_b64 v[2:3], 6, v[2:3]
	v_lshl_add_u64 v[2:3], v[0:1], 0, v[2:3]
	global_store_short v[2:3], v6, off
	v_add_u32_e32 v2, s31, v35
	v_ashrrev_i32_e32 v3, 31, v2
	v_lshlrev_b64 v[2:3], 6, v[2:3]
	s_waitcnt lgkmcnt(0)
	v_cvt_pk_bf16_f32 v4, v4, s0
	v_lshl_add_u64 v[2:3], v[0:1], 0, v[2:3]
	global_store_short v[2:3], v4, off
	v_add_u32_e32 v4, s31, v36
	v_cvt_pk_bf16_f32 v9, v5, s0
	v_ashrrev_i32_e32 v5, 31, v4
	v_lshlrev_b64 v[4:5], 6, v[4:5]
	ds_read2_b32 v[2:3], v8 offset0:40 offset1:44
	ds_read2_b32 v[6:7], v8 offset0:48 offset1:52
	v_lshl_add_u64 v[4:5], v[0:1], 0, v[4:5]
	global_store_short v[4:5], v9, off
	v_add_u32_e32 v4, s31, v37
	v_ashrrev_i32_e32 v5, 31, v4
	v_lshlrev_b64 v[4:5], 6, v[4:5]
	s_waitcnt lgkmcnt(1)
	v_cvt_pk_bf16_f32 v2, v2, s0
	v_lshl_add_u64 v[4:5], v[0:1], 0, v[4:5]
	global_store_short v[4:5], v2, off
	v_add_u32_e32 v2, s31, v38
	v_cvt_pk_bf16_f32 v4, v3, s0
	v_ashrrev_i32_e32 v3, 31, v2
	v_lshlrev_b64 v[2:3], 6, v[2:3]
	v_lshl_add_u64 v[2:3], v[0:1], 0, v[2:3]
	global_store_short v[2:3], v4, off
	v_add_u32_e32 v2, s31, v39
	v_ashrrev_i32_e32 v3, 31, v2
	v_lshlrev_b64 v[2:3], 6, v[2:3]
	s_waitcnt lgkmcnt(0)
	v_cvt_pk_bf16_f32 v4, v6, s0
	v_lshl_add_u64 v[2:3], v[0:1], 0, v[2:3]
	global_store_short v[2:3], v4, off
	v_add_u32_e32 v2, s31, v40
	v_ashrrev_i32_e32 v3, 31, v2
	ds_read_b32 v5, v8 offset:224
	v_lshlrev_b64 v[2:3], 6, v[2:3]
	v_cvt_pk_bf16_f32 v4, v7, s0
	v_lshl_add_u64 v[2:3], v[0:1], 0, v[2:3]
	global_store_short v[2:3], v4, off
	v_add_u32_e32 v2, s31, v41
	v_ashrrev_i32_e32 v3, 31, v2
	v_lshlrev_b64 v[2:3], 6, v[2:3]
	s_waitcnt lgkmcnt(0)
	v_cvt_pk_bf16_f32 v4, v5, s0
	v_lshl_add_u64 v[2:3], v[0:1], 0, v[2:3]
	global_store_short v[2:3], v4, off
	v_add_u32_e32 v3, 0xf0, v8
	v_add_u32_e32 v2, s31, v42
	s_mov_b64 s[40:41], 6
	v_readlane_b32 s6, v250, 7
	v_readlane_b32 s7, v250, 8
	v_readlane_b32 s8, v250, 9
	v_readlane_b32 s9, v250, 10
	v_readlane_b32 s10, v250, 11
	v_readlane_b32 s11, v250, 12
	v_readlane_b32 s12, v250, 13
	v_readlane_b32 s13, v250, 14
	v_readlane_b32 s14, v250, 15
	v_readlane_b32 s15, v250, 16
	v_readlane_b32 s16, v250, 17
	v_readlane_b32 s17, v250, 18
	v_readlane_b32 s18, v250, 19
	v_readlane_b32 s19, v250, 20
